# v27
# speedup vs baseline: 1.3295x; 1.0110x over previous
.Lrot3_mid_l:
	s_waitcnt lgkmcnt(2)
	v_mfma_f32_16x16x32_bf16 v[126:129], v[152:155], v[132:135], v[126:129]
	v_mfma_f32_16x16x32_bf16 v[122:125], v[152:155], v[140:143], v[122:125]
	v_mfma_f32_16x16x32_bf16 v[118:121], v[152:155], v[144:147], v[118:121]
	v_mfma_f32_16x16x32_bf16 v[114:117], v[152:155], v[148:151], v[114:117]
	s_add_i32 m0, s16, 0x4000
	s_add_i32 s17, s15, 0xffff0000
	buffer_load_dwordx4 v131, s[64:67], s17 offen lds
	ds_read_b128 v[152:155], v228 offset:0x1800
	s_waitcnt lgkmcnt(2)
	v_mfma_f32_16x16x32_bf16 v[110:113], v[156:159], v[132:135], v[110:113]
	v_mfma_f32_16x16x32_bf16 v[106:109], v[156:159], v[140:143], v[106:109]
	v_mfma_f32_16x16x32_bf16 v[102:105], v[156:159], v[144:147], v[102:105]
	v_mfma_f32_16x16x32_bf16 v[98:101], v[156:159], v[148:151], v[98:101]
	s_add_i32 m0, s16, 0xc000
	s_nop 0
	buffer_load_dwordx4 v131, s[8:11], s17 offen lds
	ds_read_b128 v[156:159], v228 offset:0x2000
	s_waitcnt lgkmcnt(2)
	v_mfma_f32_16x16x32_bf16 v[94:97], v[160:163], v[132:135], v[94:97]
	v_mfma_f32_16x16x32_bf16 v[90:93], v[160:163], v[140:143], v[90:93]
	v_mfma_f32_16x16x32_bf16 v[86:89], v[160:163], v[144:147], v[86:89]
	v_mfma_f32_16x16x32_bf16 v[82:85], v[160:163], v[148:151], v[82:85]
	s_add_i32 m0, s16, 0x6000
	s_nop 0
	buffer_load_dwordx4 v131, s[64:67], s15 offen lds
	ds_read_b128 v[160:163], v228 offset:0x2800
	s_waitcnt lgkmcnt(2)
	v_mfma_f32_16x16x32_bf16 v[78:81], v[152:155], v[132:135], v[78:81]
	v_mfma_f32_16x16x32_bf16 v[74:77], v[152:155], v[140:143], v[74:77]
	v_mfma_f32_16x16x32_bf16 v[70:73], v[152:155], v[144:147], v[70:73]
	v_mfma_f32_16x16x32_bf16 v[66:69], v[152:155], v[148:151], v[66:69]
	s_add_i32 m0, s16, 0xe000
	s_nop 0
	buffer_load_dwordx4 v131, s[8:11], s15 offen lds
	ds_read_b128 v[152:155], v228 offset:0x3000
	s_waitcnt lgkmcnt(2)
	v_mfma_f32_16x16x32_bf16 v[62:65], v[156:159], v[132:135], v[62:65]
	v_mfma_f32_16x16x32_bf16 v[58:61], v[156:159], v[140:143], v[58:61]
	v_mfma_f32_16x16x32_bf16 v[54:57], v[156:159], v[144:147], v[54:57]
	v_mfma_f32_16x16x32_bf16 v[50:53], v[156:159], v[148:151], v[50:53]
	ds_read_b128 v[156:159], v228 offset:0x3800
	s_waitcnt lgkmcnt(2)
	v_xor_b32_e32 v0, 64, v229
	v_mfma_f32_16x16x32_bf16 v[46:49], v[160:163], v[132:135], v[46:49]
	v_mfma_f32_16x16x32_bf16 v[42:45], v[160:163], v[140:143], v[42:45]
	v_mfma_f32_16x16x32_bf16 v[38:41], v[160:163], v[144:147], v[38:41]
	v_mfma_f32_16x16x32_bf16 v[34:37], v[160:163], v[148:151], v[34:37]
	ds_read_b128 v[160:163], v0 offset:0
	ds_read_b128 v[164:167], v0 offset:0x800
	ds_read_b128 v[168:171], v0 offset:0x1000
	s_waitcnt lgkmcnt(4)
	v_mfma_f32_16x16x32_bf16 v[30:33], v[152:155], v[132:135], v[30:33]
	v_mfma_f32_16x16x32_bf16 v[26:29], v[152:155], v[140:143], v[26:29]
	v_mfma_f32_16x16x32_bf16 v[22:25], v[152:155], v[144:147], v[22:25]
	v_mfma_f32_16x16x32_bf16 v[18:21], v[152:155], v[148:151], v[18:21]
	ds_read_b128 v[232:235], v0 offset:0x1800
	ds_read_b128 v[172:175], v176 offset:0
	ds_read_b128 v[202:205], v176 offset:0x800
	s_waitcnt lgkmcnt(6)
	v_mfma_f32_16x16x32_bf16 v[14:17], v[156:159], v[132:135], v[14:17]
	v_mfma_f32_16x16x32_bf16 v[10:13], v[156:159], v[140:143], v[10:13]
	v_mfma_f32_16x16x32_bf16 v[6:9], v[156:159], v[144:147], v[6:9]
	v_mfma_f32_16x16x32_bf16 v[2:5], v[156:159], v[148:151], v[2:5]
	ds_read_b128 v[132:135], v176 offset:0x1000
	ds_read_b128 v[236:239], v176 offset:0x2800
	s_waitcnt lgkmcnt(3)
	v_mfma_f32_16x16x32_bf16 v[126:129], v[172:175], v[160:163], v[126:129]
	v_mfma_f32_16x16x32_bf16 v[122:125], v[172:175], v[164:167], v[122:125]
	v_mfma_f32_16x16x32_bf16 v[118:121], v[172:175], v[168:171], v[118:121]
	v_mfma_f32_16x16x32_bf16 v[114:117], v[172:175], v[232:235], v[114:117]
	ds_read_b128 v[140:143], v176 offset:0x1800
	ds_read_b128 v[240:243], v176 offset:0x3000
	s_waitcnt lgkmcnt(4)
	v_mfma_f32_16x16x32_bf16 v[110:113], v[202:205], v[160:163], v[110:113]
	v_mfma_f32_16x16x32_bf16 v[106:109], v[202:205], v[164:167], v[106:109]
	v_mfma_f32_16x16x32_bf16 v[102:105], v[202:205], v[168:171], v[102:105]
	v_mfma_f32_16x16x32_bf16 v[98:101], v[202:205], v[232:235], v[98:101]
	ds_read_b128 v[144:147], v176 offset:0x2000
	ds_read_b128 v[244:247], v176 offset:0x3800
	s_waitcnt lgkmcnt(5)
	v_mfma_f32_16x16x32_bf16 v[94:97], v[132:135], v[160:163], v[94:97]
	v_mfma_f32_16x16x32_bf16 v[90:93], v[132:135], v[164:167], v[90:93]
	v_mfma_f32_16x16x32_bf16 v[86:89], v[132:135], v[168:171], v[86:89]
	v_mfma_f32_16x16x32_bf16 v[82:85], v[132:135], v[232:235], v[82:85]
	s_waitcnt lgkmcnt(3)
	v_mfma_f32_16x16x32_bf16 v[78:81], v[140:143], v[160:163], v[78:81]
	v_mfma_f32_16x16x32_bf16 v[74:77], v[140:143], v[164:167], v[74:77]
	v_mfma_f32_16x16x32_bf16 v[70:73], v[140:143], v[168:171], v[70:73]
	v_mfma_f32_16x16x32_bf16 v[66:69], v[140:143], v[232:235], v[66:69]
	s_waitcnt lgkmcnt(1)
	v_mfma_f32_16x16x32_bf16 v[62:65], v[144:147], v[160:163], v[62:65]
	v_mfma_f32_16x16x32_bf16 v[58:61], v[144:147], v[164:167], v[58:61]
	v_mfma_f32_16x16x32_bf16 v[54:57], v[144:147], v[168:171], v[54:57]
	v_mfma_f32_16x16x32_bf16 v[50:53], v[144:147], v[232:235], v[50:53]
	s_setprio 0
	s_waitcnt lgkmcnt(0)
	s_waitcnt vmcnt(0)
	s_add_i32 s13, s13, 0x10000
	s_addk_i32 s15, 0x80
	s_cmp_eq_u32 s15, 0x30400
	s_mov_b32 s2, 0x10000
	s_barrier
	s_cbranch_scc0 .Lrot3_top_l
.Lrot3_top_n:
	v_add_u32_e32 v228, s2, v138
	v_add_u32_e32 v229, s2, v136
	ds_read_b128 v[132:135], v229 offset:0
	ds_read_b128 v[140:143], v229 offset:0x800
	ds_read_b128 v[144:147], v229 offset:0x1000
	ds_read_b128 v[148:151], v229 offset:0x1800
	ds_read_b128 v[152:155], v228 offset:0
	ds_read_b128 v[156:159], v228 offset:0x800
	s_setprio 1
	v_mfma_f32_16x16x32_bf16 v[46:49], v[236:239], v[160:163], v[46:49]
	v_mfma_f32_16x16x32_bf16 v[42:45], v[236:239], v[164:167], v[42:45]
	v_mfma_f32_16x16x32_bf16 v[38:41], v[236:239], v[168:171], v[38:41]
	v_mfma_f32_16x16x32_bf16 v[34:37], v[236:239], v[232:235], v[34:37]
	v_mfma_f32_16x16x32_bf16 v[30:33], v[240:243], v[160:163], v[30:33]
	v_mfma_f32_16x16x32_bf16 v[26:29], v[240:243], v[164:167], v[26:29]
	v_mfma_f32_16x16x32_bf16 v[22:25], v[240:243], v[168:171], v[22:25]
	v_mfma_f32_16x16x32_bf16 v[18:21], v[240:243], v[232:235], v[18:21]
	v_mfma_f32_16x16x32_bf16 v[14:17], v[244:247], v[160:163], v[14:17]
	v_mfma_f32_16x16x32_bf16 v[10:13], v[244:247], v[164:167], v[10:13]
	v_mfma_f32_16x16x32_bf16 v[6:9], v[244:247], v[168:171], v[6:9]
	v_mfma_f32_16x16x32_bf16 v[2:5], v[244:247], v[232:235], v[2:5]
	ds_read_b128 v[160:163], v228 offset:0x1000
	v_xor_b32_e32 v176, 64, v228
	s_waitcnt lgkmcnt(2)
	v_mfma_f32_16x16x32_bf16 v[126:129], v[152:155], v[132:135], v[126:129]
	v_mfma_f32_16x16x32_bf16 v[122:125], v[152:155], v[140:143], v[122:125]
	v_mfma_f32_16x16x32_bf16 v[118:121], v[152:155], v[144:147], v[118:121]
	v_mfma_f32_16x16x32_bf16 v[114:117], v[152:155], v[148:151], v[114:117]
	ds_read_b128 v[152:155], v228 offset:0x1800
	s_waitcnt lgkmcnt(2)
	v_mfma_f32_16x16x32_bf16 v[110:113], v[156:159], v[132:135], v[110:113]
	v_mfma_f32_16x16x32_bf16 v[106:109], v[156:159], v[140:143], v[106:109]
	v_mfma_f32_16x16x32_bf16 v[102:105], v[156:159], v[144:147], v[102:105]
	v_mfma_f32_16x16x32_bf16 v[98:101], v[156:159], v[148:151], v[98:101]
	ds_read_b128 v[156:159], v228 offset:0x2000
	s_waitcnt lgkmcnt(2)
	v_mfma_f32_16x16x32_bf16 v[94:97], v[160:163], v[132:135], v[94:97]
	v_mfma_f32_16x16x32_bf16 v[90:93], v[160:163], v[140:143], v[90:93]
	v_mfma_f32_16x16x32_bf16 v[86:89], v[160:163], v[144:147], v[86:89]
	v_mfma_f32_16x16x32_bf16 v[82:85], v[160:163], v[148:151], v[82:85]
	ds_read_b128 v[160:163], v228 offset:0x2800
	s_waitcnt lgkmcnt(2)
	v_mfma_f32_16x16x32_bf16 v[78:81], v[152:155], v[132:135], v[78:81]
	v_mfma_f32_16x16x32_bf16 v[74:77], v[152:155], v[140:143], v[74:77]
	v_mfma_f32_16x16x32_bf16 v[70:73], v[152:155], v[144:147], v[70:73]
	v_mfma_f32_16x16x32_bf16 v[66:69], v[152:155], v[148:151], v[66:69]
	ds_read_b128 v[152:155], v228 offset:0x3000
	s_waitcnt lgkmcnt(2)
	v_mfma_f32_16x16x32_bf16 v[62:65], v[156:159], v[132:135], v[62:65]
	v_mfma_f32_16x16x32_bf16 v[58:61], v[156:159], v[140:143], v[58:61]
	v_mfma_f32_16x16x32_bf16 v[54:57], v[156:159], v[144:147], v[54:57]
	v_mfma_f32_16x16x32_bf16 v[50:53], v[156:159], v[148:151], v[50:53]
	ds_read_b128 v[156:159], v228 offset:0x3800
	s_waitcnt lgkmcnt(2)
	v_xor_b32_e32 v0, 64, v229
	v_mfma_f32_16x16x32_bf16 v[46:49], v[160:163], v[132:135], v[46:49]
	v_mfma_f32_16x16x32_bf16 v[42:45], v[160:163], v[140:143], v[42:45]
	v_mfma_f32_16x16x32_bf16 v[38:41], v[160:163], v[144:147], v[38:41]
	v_mfma_f32_16x16x32_bf16 v[34:37], v[160:163], v[148:151], v[34:37]
	ds_read_b128 v[160:163], v0 offset:0
	ds_read_b128 v[164:167], v0 offset:0x800
	ds_read_b128 v[168:171], v0 offset:0x1000
	s_waitcnt lgkmcnt(4)
	v_mfma_f32_16x16x32_bf16 v[30:33], v[152:155], v[132:135], v[30:33]
	v_mfma_f32_16x16x32_bf16 v[26:29], v[152:155], v[140:143], v[26:29]
	v_mfma_f32_16x16x32_bf16 v[22:25], v[152:155], v[144:147], v[22:25]
	v_mfma_f32_16x16x32_bf16 v[18:21], v[152:155], v[148:151], v[18:21]
	ds_read_b128 v[232:235], v0 offset:0x1800
	ds_read_b128 v[172:175], v176 offset:0
	ds_read_b128 v[202:205], v176 offset:0x800
	s_waitcnt lgkmcnt(6)
	v_mfma_f32_16x16x32_bf16 v[14:17], v[156:159], v[132:135], v[14:17]
	v_mfma_f32_16x16x32_bf16 v[10:13], v[156:159], v[140:143], v[10:13]
	v_mfma_f32_16x16x32_bf16 v[6:9], v[156:159], v[144:147], v[6:9]
	v_mfma_f32_16x16x32_bf16 v[2:5], v[156:159], v[148:151], v[2:5]
	ds_read_b128 v[132:135], v176 offset:0x1000
	ds_read_b128 v[236:239], v176 offset:0x2800
	s_waitcnt lgkmcnt(3)
	v_mfma_f32_16x16x32_bf16 v[126:129], v[172:175], v[160:163], v[126:129]
	v_mfma_f32_16x16x32_bf16 v[122:125], v[172:175], v[164:167], v[122:125]
	v_mfma_f32_16x16x32_bf16 v[118:121], v[172:175], v[168:171], v[118:121]
	v_mfma_f32_16x16x32_bf16 v[114:117], v[172:175], v[232:235], v[114:117]
	ds_read_b128 v[140:143], v176 offset:0x1800
	ds_read_b128 v[240:243], v176 offset:0x3000
	s_waitcnt lgkmcnt(4)
	v_mfma_f32_16x16x32_bf16 v[110:113], v[202:205], v[160:163], v[110:113]
	v_mfma_f32_16x16x32_bf16 v[106:109], v[202:205], v[164:167], v[106:109]
	v_mfma_f32_16x16x32_bf16 v[102:105], v[202:205], v[168:171], v[102:105]
	v_mfma_f32_16x16x32_bf16 v[98:101], v[202:205], v[232:235], v[98:101]
	ds_read_b128 v[144:147], v176 offset:0x2000
	ds_read_b128 v[244:247], v176 offset:0x3800
	s_waitcnt lgkmcnt(5)
	v_mfma_f32_16x16x32_bf16 v[94:97], v[132:135], v[160:163], v[94:97]
	v_mfma_f32_16x16x32_bf16 v[90:93], v[132:135], v[164:167], v[90:93]
	v_mfma_f32_16x16x32_bf16 v[86:89], v[132:135], v[168:171], v[86:89]
	v_mfma_f32_16x16x32_bf16 v[82:85], v[132:135], v[232:235], v[82:85]
	s_waitcnt lgkmcnt(3)
	v_mfma_f32_16x16x32_bf16 v[78:81], v[140:143], v[160:163], v[78:81]
	v_mfma_f32_16x16x32_bf16 v[74:77], v[140:143], v[164:167], v[74:77]
	v_mfma_f32_16x16x32_bf16 v[70:73], v[140:143], v[168:171], v[70:73]
	v_mfma_f32_16x16x32_bf16 v[66:69], v[140:143], v[232:235], v[66:69]
	s_waitcnt lgkmcnt(1)
	v_mfma_f32_16x16x32_bf16 v[62:65], v[144:147], v[160:163], v[62:65]
	v_mfma_f32_16x16x32_bf16 v[58:61], v[144:147], v[164:167], v[58:61]
	v_mfma_f32_16x16x32_bf16 v[54:57], v[144:147], v[168:171], v[54:57]
	v_mfma_f32_16x16x32_bf16 v[50:53], v[144:147], v[232:235], v[50:53]
	s_setprio 0
	s_waitcnt lgkmcnt(0)
	s_add_i32 s13, s13, 0x10000
	s_addk_i32 s15, 0x80
	s_barrier
	v_mfma_f32_16x16x32_bf16 v[46:49], v[236:239], v[160:163], v[46:49]
	v_mfma_f32_16x16x32_bf16 v[42:45], v[236:239], v[164:167], v[42:45]
	v_mfma_f32_16x16x32_bf16 v[38:41], v[236:239], v[168:171], v[38:41]
	v_mfma_f32_16x16x32_bf16 v[34:37], v[236:239], v[232:235], v[34:37]
	v_mfma_f32_16x16x32_bf16 v[30:33], v[240:243], v[160:163], v[30:33]
	v_mfma_f32_16x16x32_bf16 v[26:29], v[240:243], v[164:167], v[26:29]
	v_mfma_f32_16x16x32_bf16 v[22:25], v[240:243], v[168:171], v[22:25]
	v_mfma_f32_16x16x32_bf16 v[18:21], v[240:243], v[232:235], v[18:21]
	v_mfma_f32_16x16x32_bf16 v[14:17], v[244:247], v[160:163], v[14:17]
	v_mfma_f32_16x16x32_bf16 v[10:13], v[244:247], v[164:167], v[10:13]
	v_mfma_f32_16x16x32_bf16 v[6:9], v[244:247], v[168:171], v[6:9]
	v_mfma_f32_16x16x32_bf16 v[2:5], v[244:247], v[232:235], v[2:5]
	s_nop 7
	s_nop 7
	s_nop 3

.LBB0_209:
	s_lshl_b32 s2, s15, 10
	s_xor_b64 s[8:9], s[10:11], -1
	s_add_i32 s10, s41, s2
	s_mov_b32 s11, 0
	v_mov_b32_e32 v18, v48
	s_add_i32 s2, s10, s11
	v_mov_b32_e32 v19, s2
	ds_read_b128 v[34:37], v19 offset:0
	ds_read_b128 v[38:41], v19 offset:16
	ds_read_b32 v236, v19
	ds_read_b32 v237, v19
.LBB0_210:
	s_add_i32 s2, s10, s11
	v_mov_b32_e32 v19, s2
	ds_read_b128 v[228:231], v19 offset:32
	ds_read_b128 v[232:235], v19 offset:48
	v_mov_b32_e32 v20, 0
	v_mov_b32_e32 v72, 0
	v_mov_b32_e32 v42, 0
	s_waitcnt lgkmcnt(5)
	v_dot2c_f32_bf16_e32 v20, v54, v34
	v_mov_b32_e32 v21, 0
	v_mov_b32_e32 v43, 0
	v_dot2c_f32_bf16_e32 v72, v56, v34
	v_dot2c_f32_bf16_e32 v20, v55, v35
	v_dot2c_f32_bf16_e32 v42, v58, v36
	s_waitcnt lgkmcnt(4)
	v_dot2c_f32_bf16_e32 v21, v62, v38
	v_dot2c_f32_bf16_e32 v43, v67, v40
	v_dot2c_f32_bf16_e32 v72, v57, v35
	v_mov_b32_e32 v34, 0
	v_mov_b32_e32 v73, 0
	v_mov_b32_e32 v35, 0
	v_dot2c_f32_bf16_e32 v42, v59, v37
	v_dot2c_f32_bf16_e32 v21, v63, v39
	v_dot2c_f32_bf16_e32 v43, v68, v41
	v_dot2c_f32_bf16_e32 v34, v60, v36
	v_dot2c_f32_bf16_e32 v73, v64, v38
	v_dot2c_f32_bf16_e32 v35, v69, v40
	v_dot2c_f32_bf16_e32 v34, v61, v37
	v_dot2c_f32_bf16_e32 v73, v65, v39
	v_dot2c_f32_bf16_e32 v35, v70, v41
	v_pk_add_f32 v[20:21], v[20:21], v[42:43]
	v_mov_b32_e32 v42, 0
	v_add_f32_e32 v33, v20, v21
	v_pk_add_f32 v[20:21], v[72:73], v[34:35]
	v_fma_f32 v33, -v53, v66, v33
	v_add_f32_e32 v74, v20, v21
	v_fmac_f32_e32 v33, v52, v71
	v_fmac_f32_e32 v74, v53, v71
	v_cvt_pk_bf16_f32 v20, v33, v1
	v_fmac_f32_e32 v74, v52, v66
	ds_write_b16 v18, v20
	v_cvt_pk_bf16_f32 v20, v74, v1
	ds_write_b16 v18, v20 offset:128
	ds_read_b128 v[34:37], v19 offset:64
	ds_read_b128 v[38:41], v19 offset:80
	v_mov_b32_e32 v20, 0
	v_mov_b32_e32 v72, 0
	v_mov_b32_e32 v21, 0
	s_waitcnt lgkmcnt(5)
	v_dot2c_f32_bf16_e32 v20, v54, v228
	v_mov_b32_e32 v43, 0
	v_dot2c_f32_bf16_e32 v72, v56, v228
	v_dot2c_f32_bf16_e32 v20, v55, v229
	v_dot2c_f32_bf16_e32 v42, v58, v230
	s_waitcnt lgkmcnt(4)
	v_dot2c_f32_bf16_e32 v21, v62, v232
	v_dot2c_f32_bf16_e32 v43, v67, v234
	v_dot2c_f32_bf16_e32 v72, v57, v229
	v_mov_b32_e32 v228, 0
	v_mov_b32_e32 v73, 0
	v_mov_b32_e32 v229, 0
	v_dot2c_f32_bf16_e32 v42, v59, v231
	v_dot2c_f32_bf16_e32 v21, v63, v233
	v_dot2c_f32_bf16_e32 v43, v68, v235
	v_dot2c_f32_bf16_e32 v228, v60, v230
	v_dot2c_f32_bf16_e32 v73, v64, v232
	v_dot2c_f32_bf16_e32 v229, v69, v234
	v_dot2c_f32_bf16_e32 v228, v61, v231
	v_dot2c_f32_bf16_e32 v73, v65, v233
	v_dot2c_f32_bf16_e32 v229, v70, v235
	v_pk_add_f32 v[20:21], v[20:21], v[42:43]
	v_mov_b32_e32 v42, 0
	v_add_f32_e32 v230, v20, v21
	v_pk_add_f32 v[20:21], v[72:73], v[228:229]
	v_fma_f32 v71, -v53, v74, v230
	v_add_f32_e32 v66, v20, v21
	v_fmac_f32_e32 v71, v52, v33
	v_fmac_f32_e32 v66, v53, v33
	v_cvt_pk_bf16_f32 v20, v71, v1
	v_fmac_f32_e32 v66, v52, v74
	ds_write_b16 v18, v20 offset:272
	v_cvt_pk_bf16_f32 v20, v66, v1
	ds_write_b16 v18, v20 offset:400
	ds_read_b128 v[228:231], v19 offset:96
	ds_read_b128 v[232:235], v19 offset:112
	v_mov_b32_e32 v20, 0
	v_mov_b32_e32 v72, 0
	v_mov_b32_e32 v21, 0
	s_waitcnt lgkmcnt(5)
	v_dot2c_f32_bf16_e32 v20, v54, v34
	v_mov_b32_e32 v43, 0
	v_dot2c_f32_bf16_e32 v72, v56, v34
	v_dot2c_f32_bf16_e32 v20, v55, v35
	v_dot2c_f32_bf16_e32 v42, v58, v36
	s_waitcnt lgkmcnt(4)
	v_dot2c_f32_bf16_e32 v21, v62, v38
	v_dot2c_f32_bf16_e32 v43, v67, v40
	v_dot2c_f32_bf16_e32 v72, v57, v35
	v_mov_b32_e32 v34, 0
	v_mov_b32_e32 v73, 0
	v_mov_b32_e32 v35, 0
	v_dot2c_f32_bf16_e32 v42, v59, v37
	v_dot2c_f32_bf16_e32 v21, v63, v39
	v_dot2c_f32_bf16_e32 v43, v68, v41
	v_dot2c_f32_bf16_e32 v34, v60, v36
	v_dot2c_f32_bf16_e32 v73, v64, v38
	v_dot2c_f32_bf16_e32 v35, v69, v40
	v_dot2c_f32_bf16_e32 v34, v61, v37
	v_dot2c_f32_bf16_e32 v73, v65, v39
	v_dot2c_f32_bf16_e32 v35, v70, v41
	v_pk_add_f32 v[20:21], v[20:21], v[42:43]
	v_mov_b32_e32 v42, 0
	v_add_f32_e32 v33, v20, v21
	v_pk_add_f32 v[20:21], v[72:73], v[34:35]
	v_fma_f32 v33, -v53, v66, v33
	v_add_f32_e32 v74, v20, v21
	v_fmac_f32_e32 v33, v52, v71
	v_fmac_f32_e32 v74, v53, v71
	v_cvt_pk_bf16_f32 v20, v33, v1
	v_fmac_f32_e32 v74, v52, v66
	ds_write_b16 v18, v20 offset:544
	v_cvt_pk_bf16_f32 v20, v74, v1
	ds_write_b16 v18, v20 offset:672
	ds_read_b128 v[34:37], v19 offset:128
	ds_read_b128 v[38:41], v19 offset:144
	v_mov_b32_e32 v20, 0
	v_mov_b32_e32 v72, 0
	v_mov_b32_e32 v21, 0
	s_waitcnt lgkmcnt(5)
	v_dot2c_f32_bf16_e32 v20, v54, v228
	v_mov_b32_e32 v43, 0
	v_dot2c_f32_bf16_e32 v72, v56, v228
	v_dot2c_f32_bf16_e32 v20, v55, v229
	v_dot2c_f32_bf16_e32 v42, v58, v230
	s_waitcnt lgkmcnt(4)
	v_dot2c_f32_bf16_e32 v21, v62, v232
	v_dot2c_f32_bf16_e32 v43, v67, v234
	v_dot2c_f32_bf16_e32 v72, v57, v229
	v_mov_b32_e32 v228, 0
	v_mov_b32_e32 v73, 0
	v_mov_b32_e32 v229, 0
	v_dot2c_f32_bf16_e32 v42, v59, v231
	v_dot2c_f32_bf16_e32 v21, v63, v233
	v_dot2c_f32_bf16_e32 v43, v68, v235
	v_dot2c_f32_bf16_e32 v228, v60, v230
	v_dot2c_f32_bf16_e32 v73, v64, v232
	v_dot2c_f32_bf16_e32 v229, v69, v234
	v_dot2c_f32_bf16_e32 v228, v61, v231
	v_dot2c_f32_bf16_e32 v73, v65, v233
	v_dot2c_f32_bf16_e32 v229, v70, v235
	v_pk_add_f32 v[20:21], v[20:21], v[42:43]
	s_addk_i32 s11, 0x80
	v_add_f32_e32 v19, v20, v21
	v_pk_add_f32 v[20:21], v[72:73], v[228:229]
	v_fma_f32 v71, -v53, v74, v19
	v_add_f32_e32 v66, v20, v21
	v_fmac_f32_e32 v71, v52, v33
	v_fmac_f32_e32 v66, v53, v33
	v_cvt_pk_bf16_f32 v19, v71, v1
	v_fmac_f32_e32 v66, v52, v74
	ds_write_b16 v18, v19 offset:816
	v_cvt_pk_bf16_f32 v19, v66, v1
	ds_write_b16 v18, v19 offset:944
	v_add_u32_e32 v18, 0x440, v18
	s_cmpk_eq_i32 s11, 0x400
	s_cbranch_scc0 .LBB0_210
	s_waitcnt lgkmcnt(0)
	ds_read_b128 v[18:21], v51 offset:4096
	ds_read_b128 v[34:37], v51 offset:4160
	v_lshl_or_b32 v33, s15, 5, v46
	s_mov_b32 s15, 1
	s_mov_b64 s[10:11], 0
	s_and_b64 vcc, exec, s[8:9]
	s_waitcnt lgkmcnt(1)
	v_mfma_f32_16x16x32_bf16 v[18:21], v[18:21], v[2:5], 0
	s_waitcnt lgkmcnt(0)
	v_mfma_f32_16x16x32_bf16 v[18:21], v[34:37], v[6:9], v[18:21]
	ds_read_b128 v[34:37], v51 offset:4224
	s_waitcnt lgkmcnt(0)
	v_mfma_f32_16x16x32_bf16 v[18:21], v[34:37], v[10:13], v[18:21]
	ds_read_b128 v[34:37], v51 offset:4288
	s_waitcnt lgkmcnt(0)
	v_mfma_f32_16x16x32_bf16 v[18:21], v[34:37], v[14:17], v[18:21]
	v_lshl_add_u32 v34, v33, 5, v47
	ds_read_u16 v34, v34
	s_waitcnt lgkmcnt(0)
	v_lshlrev_b32_e32 v34, 16, v34
	s_nop 3
	v_fma_f32 v18, v0, v34, v18
	v_mul_f32_e32 v34, 0x3d372713, v18
	v_mul_f32_e32 v34, v18, v34
	v_fma_f32 v34, v18, v34, v18
	v_mul_f32_e32 v34, 0xbfcc422a, v34
	v_mul_f32_e32 v34, 0x3fb8aa3b, v34
	v_exp_f32_e32 v34, v34
	s_nop 0
	v_add_f32_e32 v34, 1.0, v34
	v_rcp_f32_e32 v34, v34
	s_nop 0
	v_mul_f32_e32 v18, v18, v34
	v_or_b32_e32 v34, s14, v33
	v_ashrrev_i32_e32 v35, 31, v34
	v_lshlrev_b64 v[34:35], 10, v[34:35]
	v_cvt_pk_bf16_f32 v18, v18, v1
	v_lshl_add_u64 v[34:35], v[30:31], 0, v[34:35]
	global_store_short v[34:35], v18, off
	v_or_b32_e32 v18, 1, v33
	v_lshl_add_u32 v34, v18, 5, v47
	ds_read_u16 v34, v34
	v_or_b32_e32 v18, s14, v18
	s_waitcnt lgkmcnt(0)
	v_lshlrev_b32_e32 v34, 16, v34
	v_fma_f32 v19, v0, v34, v19
	v_mul_f32_e32 v34, 0x3d372713, v19
	v_mul_f32_e32 v34, v19, v34
	v_fma_f32 v34, v19, v34, v19
	v_mul_f32_e32 v34, 0xbfcc422a, v34
	v_mul_f32_e32 v34, 0x3fb8aa3b, v34
	v_exp_f32_e32 v34, v34
	s_nop 0
	v_add_f32_e32 v34, 1.0, v34
	v_rcp_f32_e32 v34, v34
	s_nop 0
	v_mul_f32_e32 v19, v19, v34
	v_cvt_pk_bf16_f32 v34, v19, v1
	v_ashrrev_i32_e32 v19, 31, v18
	v_lshlrev_b64 v[18:19], 10, v[18:19]
	v_lshl_add_u64 v[18:19], v[30:31], 0, v[18:19]
	global_store_short v[18:19], v34, off
	v_or_b32_e32 v18, 2, v33
	v_lshl_add_u32 v19, v18, 5, v47
	ds_read_u16 v19, v19
	ds_read_b128 v[34:37], v51 offset:8512
	v_or_b32_e32 v18, s14, v18
	s_waitcnt lgkmcnt(1)
	v_lshlrev_b32_e32 v19, 16, v19
	v_fma_f32 v19, v0, v19, v20
	v_mul_f32_e32 v20, 0x3d372713, v19
	v_mul_f32_e32 v20, v19, v20
	v_fma_f32 v20, v19, v20, v19
	v_mul_f32_e32 v20, 0xbfcc422a, v20
	v_mul_f32_e32 v20, 0x3fb8aa3b, v20
	v_exp_f32_e32 v20, v20
	s_nop 0
	v_add_f32_e32 v20, 1.0, v20
	v_rcp_f32_e32 v20, v20
	s_nop 0
	v_mul_f32_e32 v19, v19, v20
	v_cvt_pk_bf16_f32 v20, v19, v1
	v_ashrrev_i32_e32 v19, 31, v18
	v_lshlrev_b64 v[18:19], 10, v[18:19]
	v_lshl_add_u64 v[18:19], v[30:31], 0, v[18:19]
	global_store_short v[18:19], v20, off
	v_or_b32_e32 v18, 3, v33
	v_lshl_add_u32 v19, v18, 5, v47
	ds_read_u16 v19, v19
	v_or_b32_e32 v18, s14, v18
	s_waitcnt lgkmcnt(0)
	v_lshlrev_b32_e32 v19, 16, v19
	v_fmac_f32_e32 v21, v0, v19
	v_mul_f32_e32 v19, 0x3d372713, v21
	v_mul_f32_e32 v19, v21, v19
	v_fma_f32 v19, v21, v19, v21
	v_mul_f32_e32 v19, 0xbfcc422a, v19
	v_mul_f32_e32 v19, 0x3fb8aa3b, v19
	v_exp_f32_e32 v19, v19
	s_nop 0
	v_add_f32_e32 v19, 1.0, v19
	v_rcp_f32_e32 v19, v19
	s_nop 0
	v_mul_f32_e32 v19, v21, v19
	v_cvt_pk_bf16_f32 v20, v19, v1
	v_ashrrev_i32_e32 v19, 31, v18
	v_lshlrev_b64 v[18:19], 10, v[18:19]
	v_lshl_add_u64 v[18:19], v[30:31], 0, v[18:19]
	global_store_short v[18:19], v20, off
	ds_read_b128 v[18:21], v51 offset:8448
	s_waitcnt lgkmcnt(0)
	v_mfma_f32_16x16x32_bf16 v[18:21], v[18:21], v[2:5], 0
	v_mfma_f32_16x16x32_bf16 v[18:21], v[34:37], v[6:9], v[18:21]
	ds_read_b128 v[34:37], v51 offset:8576
	s_waitcnt lgkmcnt(0)
	v_mfma_f32_16x16x32_bf16 v[18:21], v[34:37], v[10:13], v[18:21]
	ds_read_b128 v[34:37], v51 offset:8640
	s_waitcnt lgkmcnt(0)
	v_mfma_f32_16x16x32_bf16 v[18:21], v[34:37], v[14:17], v[18:21]
	v_or_b32_e32 v34, 16, v33
	v_lshl_add_u32 v35, v34, 5, v47
	ds_read_u16 v35, v35
	v_or_b32_e32 v34, s14, v34
	s_waitcnt lgkmcnt(0)
	v_lshlrev_b32_e32 v35, 16, v35
	s_nop 1
	v_fma_f32 v18, v0, v35, v18
	v_mul_f32_e32 v35, 0x3d372713, v18
	v_mul_f32_e32 v35, v18, v35
	v_fma_f32 v35, v18, v35, v18
	v_mul_f32_e32 v35, 0xbfcc422a, v35
	v_mul_f32_e32 v35, 0x3fb8aa3b, v35
	v_exp_f32_e32 v35, v35
	s_nop 0
	v_add_f32_e32 v35, 1.0, v35
	v_rcp_f32_e32 v35, v35
	s_nop 0
	v_mul_f32_e32 v18, v18, v35
	v_ashrrev_i32_e32 v35, 31, v34
	v_lshlrev_b64 v[34:35], 10, v[34:35]
	v_cvt_pk_bf16_f32 v18, v18, v1
	v_lshl_add_u64 v[34:35], v[30:31], 0, v[34:35]
	global_store_short v[34:35], v18, off
	v_or_b32_e32 v18, 17, v33
	v_lshl_add_u32 v34, v18, 5, v47
	ds_read_u16 v34, v34
	v_or_b32_e32 v18, s14, v18
	s_waitcnt lgkmcnt(0)
	v_lshlrev_b32_e32 v34, 16, v34
	v_fma_f32 v19, v0, v34, v19
	v_mul_f32_e32 v34, 0x3d372713, v19
	v_mul_f32_e32 v34, v19, v34
	v_fma_f32 v34, v19, v34, v19
	v_mul_f32_e32 v34, 0xbfcc422a, v34
	v_mul_f32_e32 v34, 0x3fb8aa3b, v34
	v_exp_f32_e32 v34, v34
	s_nop 0
	v_add_f32_e32 v34, 1.0, v34
	v_rcp_f32_e32 v34, v34
	s_nop 0
	v_mul_f32_e32 v19, v19, v34
	v_cvt_pk_bf16_f32 v34, v19, v1
	v_ashrrev_i32_e32 v19, 31, v18
	v_lshlrev_b64 v[18:19], 10, v[18:19]
	v_lshl_add_u64 v[18:19], v[30:31], 0, v[18:19]
	global_store_short v[18:19], v34, off
	v_or_b32_e32 v18, 18, v33
	v_lshl_add_u32 v19, v18, 5, v47
	ds_read_u16 v19, v19
	v_or_b32_e32 v18, s14, v18
	s_waitcnt lgkmcnt(0)
	v_lshlrev_b32_e32 v19, 16, v19
	v_fma_f32 v19, v0, v19, v20
	v_mul_f32_e32 v20, 0x3d372713, v19
	v_mul_f32_e32 v20, v19, v20
	v_fma_f32 v20, v19, v20, v19
	v_mul_f32_e32 v20, 0xbfcc422a, v20
	v_mul_f32_e32 v20, 0x3fb8aa3b, v20
	v_exp_f32_e32 v20, v20
	s_nop 0
	v_add_f32_e32 v20, 1.0, v20
	v_rcp_f32_e32 v20, v20
	s_nop 0
	v_mul_f32_e32 v19, v19, v20
	v_cvt_pk_bf16_f32 v20, v19, v1
	v_ashrrev_i32_e32 v19, 31, v18
	v_lshlrev_b64 v[18:19], 10, v[18:19]
	v_lshl_add_u64 v[18:19], v[30:31], 0, v[18:19]
	global_store_short v[18:19], v20, off
	v_or_b32_e32 v18, 19, v33
	v_lshl_add_u32 v19, v18, 5, v47
	ds_read_u16 v19, v19
	v_or_b32_e32 v18, s14, v18
	s_waitcnt lgkmcnt(0)
	v_lshlrev_b32_e32 v19, 16, v19
	v_fmac_f32_e32 v21, v0, v19
	v_mul_f32_e32 v19, 0x3d372713, v21
	v_mul_f32_e32 v19, v21, v19
	v_fma_f32 v19, v21, v19, v21
	v_mul_f32_e32 v19, 0xbfcc422a, v19
	v_mul_f32_e32 v19, 0x3fb8aa3b, v19
	v_exp_f32_e32 v19, v19
	s_nop 0
	v_add_f32_e32 v19, 1.0, v19
	v_rcp_f32_e32 v19, v19
	s_nop 0
	v_mul_f32_e32 v19, v21, v19
	v_cvt_pk_bf16_f32 v20, v19, v1
	v_ashrrev_i32_e32 v19, 31, v18
	v_lshlrev_b64 v[18:19], 10, v[18:19]
	v_lshl_add_u64 v[18:19], v[30:31], 0, v[18:19]
	global_store_short v[18:19], v20, off
	s_waitcnt lgkmcnt(0)
	s_cbranch_vccz .LBB0_209
	s_add_i32 s13, s13, 1
	s_cmp_eq_u32 s13, 4
	s_cbranch_scc0 .LBB0_208
	s_load_dword s2, s[78:79], 0x0
	s_waitcnt lgkmcnt(0)
	s_lshl_b32 s2, s2, 3
	s_add_i32 s40, s2, s40
	s_cmpk_gt_i32 s40, 0x7ff
	s_cbranch_scc0 .LBB0_165

.Lrot2_mid_l:
	s_waitcnt lgkmcnt(2)
	v_mfma_f32_16x16x32_bf16 v[122:125], v[146:149], v[130:133], v[122:125]
	v_mfma_f32_16x16x32_bf16 v[126:129], v[146:149], v[134:137], v[126:129]
	v_mfma_f32_16x16x32_bf16 v[118:121], v[146:149], v[138:141], v[118:121]
	v_mfma_f32_16x16x32_bf16 v[114:117], v[146:149], v[142:145], v[114:117]
	s_add_i32 m0, s51, 0x4000
	s_add_i32 s52, s21, 0xfffe0000
	buffer_load_dwordx4 v173, s[64:67], s52 offen lds
	ds_read_b128 v[146:149], v228 offset:0x1800
	s_waitcnt lgkmcnt(2)
	v_mfma_f32_16x16x32_bf16 v[110:113], v[150:153], v[130:133], v[110:113]
	v_mfma_f32_16x16x32_bf16 v[106:109], v[150:153], v[134:137], v[106:109]
	v_mfma_f32_16x16x32_bf16 v[102:105], v[150:153], v[138:141], v[102:105]
	v_mfma_f32_16x16x32_bf16 v[98:101], v[150:153], v[142:145], v[98:101]
	s_add_i32 m0, s51, 0xc000
	s_nop 0
	buffer_load_dwordx4 v248, s[8:11], s52 offen lds
	ds_read_b128 v[150:153], v228 offset:0x2000
	s_waitcnt lgkmcnt(2)
	v_mfma_f32_16x16x32_bf16 v[94:97], v[154:157], v[130:133], v[94:97]
	v_mfma_f32_16x16x32_bf16 v[90:93], v[154:157], v[134:137], v[90:93]
	v_mfma_f32_16x16x32_bf16 v[86:89], v[154:157], v[138:141], v[86:89]
	v_mfma_f32_16x16x32_bf16 v[82:85], v[154:157], v[142:145], v[82:85]
	s_add_i32 m0, s51, 0x6000
	s_nop 0
	buffer_load_dwordx4 v173, s[64:67], s21 offen lds
	ds_read_b128 v[154:157], v228 offset:0x2800
	s_waitcnt lgkmcnt(2)
	v_mfma_f32_16x16x32_bf16 v[78:81], v[146:149], v[130:133], v[78:81]
	v_mfma_f32_16x16x32_bf16 v[74:77], v[146:149], v[134:137], v[74:77]
	v_mfma_f32_16x16x32_bf16 v[70:73], v[146:149], v[138:141], v[70:73]
	v_mfma_f32_16x16x32_bf16 v[66:69], v[146:149], v[142:145], v[66:69]
	s_add_i32 m0, s51, 0xe000
	s_nop 0
	buffer_load_dwordx4 v248, s[8:11], s21 offen lds
	ds_read_b128 v[146:149], v228 offset:0x3000
	s_waitcnt lgkmcnt(2)
	v_mfma_f32_16x16x32_bf16 v[62:65], v[150:153], v[130:133], v[62:65]
	v_mfma_f32_16x16x32_bf16 v[58:61], v[150:153], v[134:137], v[58:61]
	v_mfma_f32_16x16x32_bf16 v[54:57], v[150:153], v[138:141], v[54:57]
	v_mfma_f32_16x16x32_bf16 v[50:53], v[150:153], v[142:145], v[50:53]
	ds_read_b128 v[150:153], v228 offset:0x3800
	s_waitcnt lgkmcnt(2)
	v_xor_b32_e32 v0, 64, v229
	v_mfma_f32_16x16x32_bf16 v[46:49], v[154:157], v[130:133], v[46:49]
	v_mfma_f32_16x16x32_bf16 v[42:45], v[154:157], v[134:137], v[42:45]
	v_mfma_f32_16x16x32_bf16 v[38:41], v[154:157], v[138:141], v[38:41]
	v_mfma_f32_16x16x32_bf16 v[34:37], v[154:157], v[142:145], v[34:37]
	ds_read_b128 v[154:157], v0 offset:0
	ds_read_b128 v[158:161], v0 offset:0x800
	ds_read_b128 v[162:165], v0 offset:0x1000
	s_waitcnt lgkmcnt(4)
	v_mfma_f32_16x16x32_bf16 v[30:33], v[146:149], v[130:133], v[30:33]
	v_mfma_f32_16x16x32_bf16 v[26:29], v[146:149], v[134:137], v[26:29]
	v_mfma_f32_16x16x32_bf16 v[22:25], v[146:149], v[138:141], v[22:25]
	v_mfma_f32_16x16x32_bf16 v[18:21], v[146:149], v[142:145], v[18:21]
	ds_read_b128 v[232:235], v0 offset:0x1800
	ds_read_b128 v[166:169], v177 offset:0
	ds_read_b128 v[206:209], v177 offset:0x800
	s_waitcnt lgkmcnt(6)
	v_mfma_f32_16x16x32_bf16 v[14:17], v[150:153], v[130:133], v[14:17]
	v_mfma_f32_16x16x32_bf16 v[10:13], v[150:153], v[134:137], v[10:13]
	v_mfma_f32_16x16x32_bf16 v[6:9], v[150:153], v[138:141], v[6:9]
	v_mfma_f32_16x16x32_bf16 v[2:5], v[150:153], v[142:145], v[2:5]
	ds_read_b128 v[130:133], v177 offset:0x1000
	ds_read_b128 v[236:239], v177 offset:0x2800
	s_waitcnt lgkmcnt(3)
	v_mfma_f32_16x16x32_bf16 v[122:125], v[166:169], v[154:157], v[122:125]
	v_mfma_f32_16x16x32_bf16 v[126:129], v[166:169], v[158:161], v[126:129]
	v_mfma_f32_16x16x32_bf16 v[118:121], v[166:169], v[162:165], v[118:121]
	v_mfma_f32_16x16x32_bf16 v[114:117], v[166:169], v[232:235], v[114:117]
	ds_read_b128 v[134:137], v177 offset:0x1800
	ds_read_b128 v[240:243], v177 offset:0x3000
	s_waitcnt lgkmcnt(4)
	v_mfma_f32_16x16x32_bf16 v[110:113], v[206:209], v[154:157], v[110:113]
	v_mfma_f32_16x16x32_bf16 v[106:109], v[206:209], v[158:161], v[106:109]
	v_mfma_f32_16x16x32_bf16 v[102:105], v[206:209], v[162:165], v[102:105]
	v_mfma_f32_16x16x32_bf16 v[98:101], v[206:209], v[232:235], v[98:101]
	ds_read_b128 v[138:141], v177 offset:0x2000
	ds_read_b128 v[244:247], v177 offset:0x3800
	s_waitcnt lgkmcnt(5)
	v_mfma_f32_16x16x32_bf16 v[94:97], v[130:133], v[154:157], v[94:97]
	v_mfma_f32_16x16x32_bf16 v[90:93], v[130:133], v[158:161], v[90:93]
	v_mfma_f32_16x16x32_bf16 v[86:89], v[130:133], v[162:165], v[86:89]
	v_mfma_f32_16x16x32_bf16 v[82:85], v[130:133], v[232:235], v[82:85]
	s_waitcnt lgkmcnt(3)
	v_mfma_f32_16x16x32_bf16 v[78:81], v[134:137], v[154:157], v[78:81]
	v_mfma_f32_16x16x32_bf16 v[74:77], v[134:137], v[158:161], v[74:77]
	v_mfma_f32_16x16x32_bf16 v[70:73], v[134:137], v[162:165], v[70:73]
	v_mfma_f32_16x16x32_bf16 v[66:69], v[134:137], v[232:235], v[66:69]
	s_waitcnt lgkmcnt(1)
	v_mfma_f32_16x16x32_bf16 v[62:65], v[138:141], v[154:157], v[62:65]
	v_mfma_f32_16x16x32_bf16 v[58:61], v[138:141], v[158:161], v[58:61]
	v_mfma_f32_16x16x32_bf16 v[54:57], v[138:141], v[162:165], v[54:57]
	v_mfma_f32_16x16x32_bf16 v[50:53], v[138:141], v[232:235], v[50:53]
	s_setprio 0
	s_waitcnt lgkmcnt(0)
	s_waitcnt vmcnt(0)
	s_add_i32 s19, s19, 0x10000
	s_addk_i32 s21, 0x80
	s_cmp_eq_u32 s21, 0x60800
	s_mov_b32 s2, 0x10000
	s_barrier
	s_cbranch_scc0 .Lrot2_top_l
.Lrot2_top_n:
	v_add_u32_e32 v228, s2, v205
	v_add_u32_e32 v229, s2, v202
	ds_read_b128 v[130:133], v229 offset:0
	ds_read_b128 v[134:137], v229 offset:0x800
	ds_read_b128 v[138:141], v229 offset:0x1000
	ds_read_b128 v[142:145], v229 offset:0x1800
	ds_read_b128 v[146:149], v228 offset:0
	ds_read_b128 v[150:153], v228 offset:0x800
	s_setprio 1
	v_mfma_f32_16x16x32_bf16 v[46:49], v[236:239], v[154:157], v[46:49]
	v_mfma_f32_16x16x32_bf16 v[42:45], v[236:239], v[158:161], v[42:45]
	v_mfma_f32_16x16x32_bf16 v[38:41], v[236:239], v[162:165], v[38:41]
	v_mfma_f32_16x16x32_bf16 v[34:37], v[236:239], v[232:235], v[34:37]
	v_mfma_f32_16x16x32_bf16 v[30:33], v[240:243], v[154:157], v[30:33]
	v_mfma_f32_16x16x32_bf16 v[26:29], v[240:243], v[158:161], v[26:29]
	v_mfma_f32_16x16x32_bf16 v[22:25], v[240:243], v[162:165], v[22:25]
	v_mfma_f32_16x16x32_bf16 v[18:21], v[240:243], v[232:235], v[18:21]
	v_mfma_f32_16x16x32_bf16 v[14:17], v[244:247], v[154:157], v[14:17]
	v_mfma_f32_16x16x32_bf16 v[10:13], v[244:247], v[158:161], v[10:13]
	v_mfma_f32_16x16x32_bf16 v[6:9], v[244:247], v[162:165], v[6:9]
	v_mfma_f32_16x16x32_bf16 v[2:5], v[244:247], v[232:235], v[2:5]
	ds_read_b128 v[154:157], v228 offset:0x1000
	v_xor_b32_e32 v177, 64, v228
	s_waitcnt lgkmcnt(2)
	v_mfma_f32_16x16x32_bf16 v[122:125], v[146:149], v[130:133], v[122:125]
	v_mfma_f32_16x16x32_bf16 v[126:129], v[146:149], v[134:137], v[126:129]
	v_mfma_f32_16x16x32_bf16 v[118:121], v[146:149], v[138:141], v[118:121]
	v_mfma_f32_16x16x32_bf16 v[114:117], v[146:149], v[142:145], v[114:117]
	ds_read_b128 v[146:149], v228 offset:0x1800
	s_waitcnt lgkmcnt(2)
	v_mfma_f32_16x16x32_bf16 v[110:113], v[150:153], v[130:133], v[110:113]
	v_mfma_f32_16x16x32_bf16 v[106:109], v[150:153], v[134:137], v[106:109]
	v_mfma_f32_16x16x32_bf16 v[102:105], v[150:153], v[138:141], v[102:105]
	v_mfma_f32_16x16x32_bf16 v[98:101], v[150:153], v[142:145], v[98:101]
	ds_read_b128 v[150:153], v228 offset:0x2000
	s_waitcnt lgkmcnt(2)
	v_mfma_f32_16x16x32_bf16 v[94:97], v[154:157], v[130:133], v[94:97]
	v_mfma_f32_16x16x32_bf16 v[90:93], v[154:157], v[134:137], v[90:93]
	v_mfma_f32_16x16x32_bf16 v[86:89], v[154:157], v[138:141], v[86:89]
	v_mfma_f32_16x16x32_bf16 v[82:85], v[154:157], v[142:145], v[82:85]
	ds_read_b128 v[154:157], v228 offset:0x2800
	s_waitcnt lgkmcnt(2)
	v_mfma_f32_16x16x32_bf16 v[78:81], v[146:149], v[130:133], v[78:81]
	v_mfma_f32_16x16x32_bf16 v[74:77], v[146:149], v[134:137], v[74:77]
	v_mfma_f32_16x16x32_bf16 v[70:73], v[146:149], v[138:141], v[70:73]
	v_mfma_f32_16x16x32_bf16 v[66:69], v[146:149], v[142:145], v[66:69]
	ds_read_b128 v[146:149], v228 offset:0x3000
	s_waitcnt lgkmcnt(2)
	v_mfma_f32_16x16x32_bf16 v[62:65], v[150:153], v[130:133], v[62:65]
	v_mfma_f32_16x16x32_bf16 v[58:61], v[150:153], v[134:137], v[58:61]
	v_mfma_f32_16x16x32_bf16 v[54:57], v[150:153], v[138:141], v[54:57]
	v_mfma_f32_16x16x32_bf16 v[50:53], v[150:153], v[142:145], v[50:53]
	ds_read_b128 v[150:153], v228 offset:0x3800
	s_waitcnt lgkmcnt(2)
	v_xor_b32_e32 v0, 64, v229
	v_mfma_f32_16x16x32_bf16 v[46:49], v[154:157], v[130:133], v[46:49]
	v_mfma_f32_16x16x32_bf16 v[42:45], v[154:157], v[134:137], v[42:45]
	v_mfma_f32_16x16x32_bf16 v[38:41], v[154:157], v[138:141], v[38:41]
	v_mfma_f32_16x16x32_bf16 v[34:37], v[154:157], v[142:145], v[34:37]
	ds_read_b128 v[154:157], v0 offset:0
	ds_read_b128 v[158:161], v0 offset:0x800
	ds_read_b128 v[162:165], v0 offset:0x1000
	s_waitcnt lgkmcnt(4)
	v_mfma_f32_16x16x32_bf16 v[30:33], v[146:149], v[130:133], v[30:33]
	v_mfma_f32_16x16x32_bf16 v[26:29], v[146:149], v[134:137], v[26:29]
	v_mfma_f32_16x16x32_bf16 v[22:25], v[146:149], v[138:141], v[22:25]
	v_mfma_f32_16x16x32_bf16 v[18:21], v[146:149], v[142:145], v[18:21]
	ds_read_b128 v[232:235], v0 offset:0x1800
	ds_read_b128 v[166:169], v177 offset:0
	ds_read_b128 v[206:209], v177 offset:0x800
	s_waitcnt lgkmcnt(6)
	v_mfma_f32_16x16x32_bf16 v[14:17], v[150:153], v[130:133], v[14:17]
	v_mfma_f32_16x16x32_bf16 v[10:13], v[150:153], v[134:137], v[10:13]
	v_mfma_f32_16x16x32_bf16 v[6:9], v[150:153], v[138:141], v[6:9]
	v_mfma_f32_16x16x32_bf16 v[2:5], v[150:153], v[142:145], v[2:5]
	ds_read_b128 v[130:133], v177 offset:0x1000
	ds_read_b128 v[236:239], v177 offset:0x2800
	s_waitcnt lgkmcnt(3)
	v_mfma_f32_16x16x32_bf16 v[122:125], v[166:169], v[154:157], v[122:125]
	v_mfma_f32_16x16x32_bf16 v[126:129], v[166:169], v[158:161], v[126:129]
	v_mfma_f32_16x16x32_bf16 v[118:121], v[166:169], v[162:165], v[118:121]
	v_mfma_f32_16x16x32_bf16 v[114:117], v[166:169], v[232:235], v[114:117]
	ds_read_b128 v[134:137], v177 offset:0x1800
	ds_read_b128 v[240:243], v177 offset:0x3000
	s_waitcnt lgkmcnt(4)
	v_mfma_f32_16x16x32_bf16 v[110:113], v[206:209], v[154:157], v[110:113]
	v_mfma_f32_16x16x32_bf16 v[106:109], v[206:209], v[158:161], v[106:109]
	v_mfma_f32_16x16x32_bf16 v[102:105], v[206:209], v[162:165], v[102:105]
	v_mfma_f32_16x16x32_bf16 v[98:101], v[206:209], v[232:235], v[98:101]
	ds_read_b128 v[138:141], v177 offset:0x2000
	ds_read_b128 v[244:247], v177 offset:0x3800
	s_waitcnt lgkmcnt(5)
	v_mfma_f32_16x16x32_bf16 v[94:97], v[130:133], v[154:157], v[94:97]
	v_mfma_f32_16x16x32_bf16 v[90:93], v[130:133], v[158:161], v[90:93]
	v_mfma_f32_16x16x32_bf16 v[86:89], v[130:133], v[162:165], v[86:89]
	v_mfma_f32_16x16x32_bf16 v[82:85], v[130:133], v[232:235], v[82:85]
	s_waitcnt lgkmcnt(3)
	v_mfma_f32_16x16x32_bf16 v[78:81], v[134:137], v[154:157], v[78:81]
	v_mfma_f32_16x16x32_bf16 v[74:77], v[134:137], v[158:161], v[74:77]
	v_mfma_f32_16x16x32_bf16 v[70:73], v[134:137], v[162:165], v[70:73]
	v_mfma_f32_16x16x32_bf16 v[66:69], v[134:137], v[232:235], v[66:69]
	s_waitcnt lgkmcnt(1)
	v_mfma_f32_16x16x32_bf16 v[62:65], v[138:141], v[154:157], v[62:65]
	v_mfma_f32_16x16x32_bf16 v[58:61], v[138:141], v[158:161], v[58:61]
	v_mfma_f32_16x16x32_bf16 v[54:57], v[138:141], v[162:165], v[54:57]
	v_mfma_f32_16x16x32_bf16 v[50:53], v[138:141], v[232:235], v[50:53]
	s_setprio 0
	s_waitcnt lgkmcnt(0)
	s_add_i32 s19, s19, 0x10000
	s_addk_i32 s21, 0x80
	s_barrier
	v_mfma_f32_16x16x32_bf16 v[46:49], v[236:239], v[154:157], v[46:49]
	v_mfma_f32_16x16x32_bf16 v[42:45], v[236:239], v[158:161], v[42:45]
	v_mfma_f32_16x16x32_bf16 v[38:41], v[236:239], v[162:165], v[38:41]
	v_mfma_f32_16x16x32_bf16 v[34:37], v[236:239], v[232:235], v[34:37]
	v_mfma_f32_16x16x32_bf16 v[30:33], v[240:243], v[154:157], v[30:33]
	v_mfma_f32_16x16x32_bf16 v[26:29], v[240:243], v[158:161], v[26:29]
	v_mfma_f32_16x16x32_bf16 v[22:25], v[240:243], v[162:165], v[22:25]
	v_mfma_f32_16x16x32_bf16 v[18:21], v[240:243], v[232:235], v[18:21]
	v_mfma_f32_16x16x32_bf16 v[14:17], v[244:247], v[154:157], v[14:17]
	v_mfma_f32_16x16x32_bf16 v[10:13], v[244:247], v[158:161], v[10:13]
	v_mfma_f32_16x16x32_bf16 v[6:9], v[244:247], v[162:165], v[6:9]
	v_mfma_f32_16x16x32_bf16 v[2:5], v[244:247], v[232:235], v[2:5]
	s_nop 7
	s_nop 7
	s_nop 3

.Lrot1_mid_l:
	s_waitcnt lgkmcnt(2)
	v_mfma_f32_16x16x32_bf16 v[126:129], v[152:155], v[134:137], v[126:129]
	v_mfma_f32_16x16x32_bf16 v[122:125], v[152:155], v[138:141], v[122:125]
	v_mfma_f32_16x16x32_bf16 v[118:121], v[152:155], v[144:147], v[118:121]
	v_mfma_f32_16x16x32_bf16 v[114:117], v[152:155], v[148:151], v[114:117]
	s_add_i32 m0, s46, 0x4000
	s_add_i32 s47, s34, s45
	buffer_load_dwordx4 v131, s[64:67], s47 offen lds
	ds_read_b128 v[152:155], v228 offset:0x1800
	s_waitcnt lgkmcnt(2)
	v_mfma_f32_16x16x32_bf16 v[110:113], v[156:159], v[134:137], v[110:113]
	v_mfma_f32_16x16x32_bf16 v[106:109], v[156:159], v[138:141], v[106:109]
	v_mfma_f32_16x16x32_bf16 v[102:105], v[156:159], v[144:147], v[102:105]
	v_mfma_f32_16x16x32_bf16 v[98:101], v[156:159], v[148:151], v[98:101]
	s_add_i32 m0, s46, 0xc000
	s_nop 0
	buffer_load_dwordx4 v248, s[12:15], s47 offen lds
	ds_read_b128 v[156:159], v228 offset:0x2000
	s_waitcnt lgkmcnt(2)
	v_mfma_f32_16x16x32_bf16 v[94:97], v[160:163], v[134:137], v[94:97]
	v_mfma_f32_16x16x32_bf16 v[90:93], v[160:163], v[138:141], v[90:93]
	v_mfma_f32_16x16x32_bf16 v[86:89], v[160:163], v[144:147], v[86:89]
	v_mfma_f32_16x16x32_bf16 v[82:85], v[160:163], v[148:151], v[82:85]
	s_add_i32 m0, s46, 0x6000
	s_add_i32 s47, s37, s45
	buffer_load_dwordx4 v131, s[64:67], s47 offen lds
	ds_read_b128 v[160:163], v228 offset:0x2800
	s_waitcnt lgkmcnt(2)
	v_mfma_f32_16x16x32_bf16 v[78:81], v[152:155], v[134:137], v[78:81]
	v_mfma_f32_16x16x32_bf16 v[74:77], v[152:155], v[138:141], v[74:77]
	v_mfma_f32_16x16x32_bf16 v[70:73], v[152:155], v[144:147], v[70:73]
	v_mfma_f32_16x16x32_bf16 v[66:69], v[152:155], v[148:151], v[66:69]
	s_add_i32 m0, s46, 0xe000
	s_nop 0
	buffer_load_dwordx4 v248, s[12:15], s47 offen lds
	ds_read_b128 v[152:155], v228 offset:0x3000
	s_waitcnt lgkmcnt(2)
	v_mfma_f32_16x16x32_bf16 v[62:65], v[156:159], v[134:137], v[62:65]
	v_mfma_f32_16x16x32_bf16 v[58:61], v[156:159], v[138:141], v[58:61]
	v_mfma_f32_16x16x32_bf16 v[54:57], v[156:159], v[144:147], v[54:57]
	v_mfma_f32_16x16x32_bf16 v[50:53], v[156:159], v[148:151], v[50:53]
	ds_read_b128 v[156:159], v228 offset:0x3800
	s_waitcnt lgkmcnt(2)
	v_xor_b32_e32 v0, 64, v229
	v_mfma_f32_16x16x32_bf16 v[46:49], v[160:163], v[134:137], v[46:49]
	v_mfma_f32_16x16x32_bf16 v[42:45], v[160:163], v[138:141], v[42:45]
	v_mfma_f32_16x16x32_bf16 v[38:41], v[160:163], v[144:147], v[38:41]
	v_mfma_f32_16x16x32_bf16 v[34:37], v[160:163], v[148:151], v[34:37]
	ds_read_b128 v[160:163], v0 offset:0
	ds_read_b128 v[164:167], v0 offset:0x800
	ds_read_b128 v[168:171], v0 offset:0x1000
	s_waitcnt lgkmcnt(4)
	v_mfma_f32_16x16x32_bf16 v[30:33], v[152:155], v[134:137], v[30:33]
	v_mfma_f32_16x16x32_bf16 v[26:29], v[152:155], v[138:141], v[26:29]
	v_mfma_f32_16x16x32_bf16 v[22:25], v[152:155], v[144:147], v[22:25]
	v_mfma_f32_16x16x32_bf16 v[18:21], v[152:155], v[148:151], v[18:21]
	ds_read_b128 v[232:235], v0 offset:0x1800
	ds_read_b128 v[172:175], v176 offset:0
	ds_read_b128 v[202:205], v176 offset:0x800
	s_waitcnt lgkmcnt(6)
	v_mfma_f32_16x16x32_bf16 v[14:17], v[156:159], v[134:137], v[14:17]
	v_mfma_f32_16x16x32_bf16 v[10:13], v[156:159], v[138:141], v[10:13]
	v_mfma_f32_16x16x32_bf16 v[6:9], v[156:159], v[144:147], v[6:9]
	v_mfma_f32_16x16x32_bf16 v[2:5], v[156:159], v[148:151], v[2:5]
	ds_read_b128 v[134:137], v176 offset:0x1000
	ds_read_b128 v[236:239], v176 offset:0x2800
	s_waitcnt lgkmcnt(3)
	v_mfma_f32_16x16x32_bf16 v[126:129], v[172:175], v[160:163], v[126:129]
	v_mfma_f32_16x16x32_bf16 v[122:125], v[172:175], v[164:167], v[122:125]
	v_mfma_f32_16x16x32_bf16 v[118:121], v[172:175], v[168:171], v[118:121]
	v_mfma_f32_16x16x32_bf16 v[114:117], v[172:175], v[232:235], v[114:117]
	ds_read_b128 v[138:141], v176 offset:0x1800
	ds_read_b128 v[240:243], v176 offset:0x3000
	s_waitcnt lgkmcnt(4)
	v_mfma_f32_16x16x32_bf16 v[110:113], v[202:205], v[160:163], v[110:113]
	v_mfma_f32_16x16x32_bf16 v[106:109], v[202:205], v[164:167], v[106:109]
	v_mfma_f32_16x16x32_bf16 v[102:105], v[202:205], v[168:171], v[102:105]
	v_mfma_f32_16x16x32_bf16 v[98:101], v[202:205], v[232:235], v[98:101]
	ds_read_b128 v[144:147], v176 offset:0x2000
	ds_read_b128 v[244:247], v176 offset:0x3800
	s_waitcnt lgkmcnt(5)
	v_mfma_f32_16x16x32_bf16 v[94:97], v[134:137], v[160:163], v[94:97]
	v_mfma_f32_16x16x32_bf16 v[90:93], v[134:137], v[164:167], v[90:93]
	v_mfma_f32_16x16x32_bf16 v[86:89], v[134:137], v[168:171], v[86:89]
	v_mfma_f32_16x16x32_bf16 v[82:85], v[134:137], v[232:235], v[82:85]
	s_waitcnt lgkmcnt(3)
	v_mfma_f32_16x16x32_bf16 v[78:81], v[138:141], v[160:163], v[78:81]
	v_mfma_f32_16x16x32_bf16 v[74:77], v[138:141], v[164:167], v[74:77]
	v_mfma_f32_16x16x32_bf16 v[70:73], v[138:141], v[168:171], v[70:73]
	v_mfma_f32_16x16x32_bf16 v[66:69], v[138:141], v[232:235], v[66:69]
	s_waitcnt lgkmcnt(1)
	v_mfma_f32_16x16x32_bf16 v[62:65], v[144:147], v[160:163], v[62:65]
	v_mfma_f32_16x16x32_bf16 v[58:61], v[144:147], v[164:167], v[58:61]
	v_mfma_f32_16x16x32_bf16 v[54:57], v[144:147], v[168:171], v[54:57]
	v_mfma_f32_16x16x32_bf16 v[50:53], v[144:147], v[232:235], v[50:53]
	s_setprio 0
	s_waitcnt lgkmcnt(0)
	s_waitcnt vmcnt(0)
	s_add_i32 s44, s44, 0x10000
	s_addk_i32 s45, 0x80
	s_add_i32 s41, s41, 1
	s_and_b32 s2, s44, 0x10000
	s_cmp_ge_u32 s41, s24
	s_barrier
	s_cbranch_scc0 .Lrot1_top_l
.Lrot1_top_n:
	v_add_u32_e32 v228, s2, v143
	v_add_u32_e32 v229, s2, v133
	ds_read_b128 v[134:137], v229 offset:0
	ds_read_b128 v[138:141], v229 offset:0x800
	ds_read_b128 v[144:147], v229 offset:0x1000
	ds_read_b128 v[148:151], v229 offset:0x1800
	ds_read_b128 v[152:155], v228 offset:0
	ds_read_b128 v[156:159], v228 offset:0x800
	s_setprio 1
	v_mfma_f32_16x16x32_bf16 v[46:49], v[236:239], v[160:163], v[46:49]
	v_mfma_f32_16x16x32_bf16 v[42:45], v[236:239], v[164:167], v[42:45]
	v_mfma_f32_16x16x32_bf16 v[38:41], v[236:239], v[168:171], v[38:41]
	v_mfma_f32_16x16x32_bf16 v[34:37], v[236:239], v[232:235], v[34:37]
	v_mfma_f32_16x16x32_bf16 v[30:33], v[240:243], v[160:163], v[30:33]
	v_mfma_f32_16x16x32_bf16 v[26:29], v[240:243], v[164:167], v[26:29]
	v_mfma_f32_16x16x32_bf16 v[22:25], v[240:243], v[168:171], v[22:25]
	v_mfma_f32_16x16x32_bf16 v[18:21], v[240:243], v[232:235], v[18:21]
	v_mfma_f32_16x16x32_bf16 v[14:17], v[244:247], v[160:163], v[14:17]
	v_mfma_f32_16x16x32_bf16 v[10:13], v[244:247], v[164:167], v[10:13]
	v_mfma_f32_16x16x32_bf16 v[6:9], v[244:247], v[168:171], v[6:9]
	v_mfma_f32_16x16x32_bf16 v[2:5], v[244:247], v[232:235], v[2:5]
	ds_read_b128 v[160:163], v228 offset:0x1000
	v_xor_b32_e32 v176, 64, v228
	s_waitcnt lgkmcnt(2)
	v_mfma_f32_16x16x32_bf16 v[126:129], v[152:155], v[134:137], v[126:129]
	v_mfma_f32_16x16x32_bf16 v[122:125], v[152:155], v[138:141], v[122:125]
	v_mfma_f32_16x16x32_bf16 v[118:121], v[152:155], v[144:147], v[118:121]
	v_mfma_f32_16x16x32_bf16 v[114:117], v[152:155], v[148:151], v[114:117]
	ds_read_b128 v[152:155], v228 offset:0x1800
	s_waitcnt lgkmcnt(2)
	v_mfma_f32_16x16x32_bf16 v[110:113], v[156:159], v[134:137], v[110:113]
	v_mfma_f32_16x16x32_bf16 v[106:109], v[156:159], v[138:141], v[106:109]
	v_mfma_f32_16x16x32_bf16 v[102:105], v[156:159], v[144:147], v[102:105]
	v_mfma_f32_16x16x32_bf16 v[98:101], v[156:159], v[148:151], v[98:101]
	ds_read_b128 v[156:159], v228 offset:0x2000
	s_waitcnt lgkmcnt(2)
	v_mfma_f32_16x16x32_bf16 v[94:97], v[160:163], v[134:137], v[94:97]
	v_mfma_f32_16x16x32_bf16 v[90:93], v[160:163], v[138:141], v[90:93]
	v_mfma_f32_16x16x32_bf16 v[86:89], v[160:163], v[144:147], v[86:89]
	v_mfma_f32_16x16x32_bf16 v[82:85], v[160:163], v[148:151], v[82:85]
	ds_read_b128 v[160:163], v228 offset:0x2800
	s_waitcnt lgkmcnt(2)
	v_mfma_f32_16x16x32_bf16 v[78:81], v[152:155], v[134:137], v[78:81]
	v_mfma_f32_16x16x32_bf16 v[74:77], v[152:155], v[138:141], v[74:77]
	v_mfma_f32_16x16x32_bf16 v[70:73], v[152:155], v[144:147], v[70:73]
	v_mfma_f32_16x16x32_bf16 v[66:69], v[152:155], v[148:151], v[66:69]
	ds_read_b128 v[152:155], v228 offset:0x3000
	s_waitcnt lgkmcnt(2)
	v_mfma_f32_16x16x32_bf16 v[62:65], v[156:159], v[134:137], v[62:65]
	v_mfma_f32_16x16x32_bf16 v[58:61], v[156:159], v[138:141], v[58:61]
	v_mfma_f32_16x16x32_bf16 v[54:57], v[156:159], v[144:147], v[54:57]
	v_mfma_f32_16x16x32_bf16 v[50:53], v[156:159], v[148:151], v[50:53]
	ds_read_b128 v[156:159], v228 offset:0x3800
	s_waitcnt lgkmcnt(2)
	v_xor_b32_e32 v0, 64, v229
	v_mfma_f32_16x16x32_bf16 v[46:49], v[160:163], v[134:137], v[46:49]
	v_mfma_f32_16x16x32_bf16 v[42:45], v[160:163], v[138:141], v[42:45]
	v_mfma_f32_16x16x32_bf16 v[38:41], v[160:163], v[144:147], v[38:41]
	v_mfma_f32_16x16x32_bf16 v[34:37], v[160:163], v[148:151], v[34:37]
	ds_read_b128 v[160:163], v0 offset:0
	ds_read_b128 v[164:167], v0 offset:0x800
	ds_read_b128 v[168:171], v0 offset:0x1000
	s_waitcnt lgkmcnt(4)
	v_mfma_f32_16x16x32_bf16 v[30:33], v[152:155], v[134:137], v[30:33]
	v_mfma_f32_16x16x32_bf16 v[26:29], v[152:155], v[138:141], v[26:29]
	v_mfma_f32_16x16x32_bf16 v[22:25], v[152:155], v[144:147], v[22:25]
	v_mfma_f32_16x16x32_bf16 v[18:21], v[152:155], v[148:151], v[18:21]
	ds_read_b128 v[232:235], v0 offset:0x1800
	ds_read_b128 v[172:175], v176 offset:0
	ds_read_b128 v[202:205], v176 offset:0x800
	s_waitcnt lgkmcnt(6)
	v_mfma_f32_16x16x32_bf16 v[14:17], v[156:159], v[134:137], v[14:17]
	v_mfma_f32_16x16x32_bf16 v[10:13], v[156:159], v[138:141], v[10:13]
	v_mfma_f32_16x16x32_bf16 v[6:9], v[156:159], v[144:147], v[6:9]
	v_mfma_f32_16x16x32_bf16 v[2:5], v[156:159], v[148:151], v[2:5]
	ds_read_b128 v[134:137], v176 offset:0x1000
	ds_read_b128 v[236:239], v176 offset:0x2800
	s_waitcnt lgkmcnt(3)
	v_mfma_f32_16x16x32_bf16 v[126:129], v[172:175], v[160:163], v[126:129]
	v_mfma_f32_16x16x32_bf16 v[122:125], v[172:175], v[164:167], v[122:125]
	v_mfma_f32_16x16x32_bf16 v[118:121], v[172:175], v[168:171], v[118:121]
	v_mfma_f32_16x16x32_bf16 v[114:117], v[172:175], v[232:235], v[114:117]
	ds_read_b128 v[138:141], v176 offset:0x1800
	ds_read_b128 v[240:243], v176 offset:0x3000
	s_waitcnt lgkmcnt(4)
	v_mfma_f32_16x16x32_bf16 v[110:113], v[202:205], v[160:163], v[110:113]
	v_mfma_f32_16x16x32_bf16 v[106:109], v[202:205], v[164:167], v[106:109]
	v_mfma_f32_16x16x32_bf16 v[102:105], v[202:205], v[168:171], v[102:105]
	v_mfma_f32_16x16x32_bf16 v[98:101], v[202:205], v[232:235], v[98:101]
	ds_read_b128 v[144:147], v176 offset:0x2000
	ds_read_b128 v[244:247], v176 offset:0x3800
	s_waitcnt lgkmcnt(5)
	v_mfma_f32_16x16x32_bf16 v[94:97], v[134:137], v[160:163], v[94:97]
	v_mfma_f32_16x16x32_bf16 v[90:93], v[134:137], v[164:167], v[90:93]
	v_mfma_f32_16x16x32_bf16 v[86:89], v[134:137], v[168:171], v[86:89]
	v_mfma_f32_16x16x32_bf16 v[82:85], v[134:137], v[232:235], v[82:85]
	s_waitcnt lgkmcnt(3)
	v_mfma_f32_16x16x32_bf16 v[78:81], v[138:141], v[160:163], v[78:81]
	v_mfma_f32_16x16x32_bf16 v[74:77], v[138:141], v[164:167], v[74:77]
	v_mfma_f32_16x16x32_bf16 v[70:73], v[138:141], v[168:171], v[70:73]
	v_mfma_f32_16x16x32_bf16 v[66:69], v[138:141], v[232:235], v[66:69]
	s_waitcnt lgkmcnt(1)
	v_mfma_f32_16x16x32_bf16 v[62:65], v[144:147], v[160:163], v[62:65]
	v_mfma_f32_16x16x32_bf16 v[58:61], v[144:147], v[164:167], v[58:61]
	v_mfma_f32_16x16x32_bf16 v[54:57], v[144:147], v[168:171], v[54:57]
	v_mfma_f32_16x16x32_bf16 v[50:53], v[144:147], v[232:235], v[50:53]
	s_setprio 0
	s_waitcnt lgkmcnt(0)
	s_add_i32 s44, s44, 0x10000
	s_addk_i32 s45, 0x80
	s_add_i32 s41, s41, 1
	s_barrier
	v_mfma_f32_16x16x32_bf16 v[46:49], v[236:239], v[160:163], v[46:49]
	v_mfma_f32_16x16x32_bf16 v[42:45], v[236:239], v[164:167], v[42:45]
	v_mfma_f32_16x16x32_bf16 v[38:41], v[236:239], v[168:171], v[38:41]
	v_mfma_f32_16x16x32_bf16 v[34:37], v[236:239], v[232:235], v[34:37]
	v_mfma_f32_16x16x32_bf16 v[30:33], v[240:243], v[160:163], v[30:33]
	v_mfma_f32_16x16x32_bf16 v[26:29], v[240:243], v[164:167], v[26:29]
	v_mfma_f32_16x16x32_bf16 v[22:25], v[240:243], v[168:171], v[22:25]
	v_mfma_f32_16x16x32_bf16 v[18:21], v[240:243], v[232:235], v[18:21]
	v_mfma_f32_16x16x32_bf16 v[14:17], v[244:247], v[160:163], v[14:17]
	v_mfma_f32_16x16x32_bf16 v[10:13], v[244:247], v[164:167], v[10:13]
	v_mfma_f32_16x16x32_bf16 v[6:9], v[244:247], v[168:171], v[6:9]
	v_mfma_f32_16x16x32_bf16 v[2:5], v[244:247], v[232:235], v[2:5]
	s_nop 7
	s_nop 7
	s_nop 3

.Lrot0_mid_l:
	s_waitcnt lgkmcnt(2)
	v_mfma_f32_16x16x32_bf16 v[150:153], v[98:101], v[50:53], v[150:153]
	v_mfma_f32_16x16x32_bf16 v[154:157], v[98:101], v[54:57], v[154:157]
	v_mfma_f32_16x16x32_bf16 v[142:145], v[98:101], v[58:61], v[142:145]
	v_mfma_f32_16x16x32_bf16 v[98:101], v[98:101], v[78:81], v[146:149]
	s_add_i32 m0, s35, 0x4000
	s_add_i32 s36, s15, 0xfffe0000
	buffer_load_dwordx4 v201, s[64:67], s36 offen lds
	ds_read_b128 v[146:149], v228 offset:0x1800
	s_waitcnt lgkmcnt(2)
	v_mfma_f32_16x16x32_bf16 v[130:133], v[118:121], v[50:53], v[130:133]
	v_mfma_f32_16x16x32_bf16 v[134:137], v[118:121], v[54:57], v[134:137]
	v_mfma_f32_16x16x32_bf16 v[122:125], v[118:121], v[58:61], v[122:125]
	v_mfma_f32_16x16x32_bf16 v[118:121], v[118:121], v[78:81], v[126:129]
	s_add_i32 m0, s35, 0xc000
	s_nop 0
	buffer_load_dwordx4 v248, s[8:11], s36 offen lds
	ds_read_b128 v[126:129], v228 offset:0x2000
	s_waitcnt lgkmcnt(2)
	v_mfma_f32_16x16x32_bf16 v[110:113], v[138:141], v[50:53], v[110:113]
	v_mfma_f32_16x16x32_bf16 v[114:117], v[138:141], v[54:57], v[114:117]
	v_mfma_f32_16x16x32_bf16 v[102:105], v[138:141], v[58:61], v[102:105]
	v_mfma_f32_16x16x32_bf16 v[106:109], v[138:141], v[78:81], v[106:109]
	s_add_i32 m0, s35, 0x6000
	s_nop 0
	buffer_load_dwordx4 v201, s[64:67], s15 offen lds
	ds_read_b128 v[138:141], v228 offset:0x2800
	s_waitcnt lgkmcnt(2)
	v_mfma_f32_16x16x32_bf16 v[90:93], v[146:149], v[50:53], v[90:93]
	v_mfma_f32_16x16x32_bf16 v[94:97], v[146:149], v[54:57], v[94:97]
	v_mfma_f32_16x16x32_bf16 v[82:85], v[146:149], v[58:61], v[82:85]
	v_mfma_f32_16x16x32_bf16 v[86:89], v[146:149], v[78:81], v[86:89]
	s_add_i32 m0, s35, 0xe000
	s_nop 0
	buffer_load_dwordx4 v248, s[8:11], s15 offen lds
	ds_read_b128 v[146:149], v228 offset:0x3000
	s_waitcnt lgkmcnt(2)
	v_mfma_f32_16x16x32_bf16 v[70:73], v[126:129], v[50:53], v[70:73]
	v_mfma_f32_16x16x32_bf16 v[74:77], v[126:129], v[54:57], v[74:77]
	v_mfma_f32_16x16x32_bf16 v[62:65], v[126:129], v[58:61], v[62:65]
	v_mfma_f32_16x16x32_bf16 v[66:69], v[126:129], v[78:81], v[66:69]
	ds_read_b128 v[126:129], v228 offset:0x3800
	s_waitcnt lgkmcnt(2)
	v_xor_b32_e32 v166, 64, v229
	v_mfma_f32_16x16x32_bf16 v[42:45], v[138:141], v[50:53], v[42:45]
	v_mfma_f32_16x16x32_bf16 v[46:49], v[138:141], v[54:57], v[46:49]
	v_mfma_f32_16x16x32_bf16 v[34:37], v[138:141], v[58:61], v[34:37]
	v_mfma_f32_16x16x32_bf16 v[38:41], v[138:141], v[78:81], v[38:41]
	ds_read_b128 v[138:141], v166 offset:0
	ds_read_b128 v[158:161], v166 offset:0x800
	ds_read_b128 v[162:165], v166 offset:0x1000
	s_waitcnt lgkmcnt(4)
	v_mfma_f32_16x16x32_bf16 v[26:29], v[146:149], v[50:53], v[26:29]
	v_mfma_f32_16x16x32_bf16 v[30:33], v[146:149], v[54:57], v[30:33]
	v_mfma_f32_16x16x32_bf16 v[18:21], v[146:149], v[58:61], v[18:21]
	v_mfma_f32_16x16x32_bf16 v[22:25], v[146:149], v[78:81], v[22:25]
	ds_read_b128 v[166:169], v166 offset:0x1800
	ds_read_b128 v[146:149], v208 offset:0
	ds_read_b128 v[174:177], v208 offset:0x800
	s_waitcnt lgkmcnt(6)
	v_mfma_f32_16x16x32_bf16 v[10:13], v[126:129], v[50:53], v[10:13]
	v_mfma_f32_16x16x32_bf16 v[14:17], v[126:129], v[54:57], v[14:17]
	v_mfma_f32_16x16x32_bf16 v[2:5], v[126:129], v[58:61], v[2:5]
	v_mfma_f32_16x16x32_bf16 v[6:9], v[126:129], v[78:81], v[6:9]
	ds_read_b128 v[50:53], v208 offset:0x1000
	ds_read_b128 v[232:235], v208 offset:0x2800
	s_waitcnt lgkmcnt(3)
	v_mfma_f32_16x16x32_bf16 v[150:153], v[146:149], v[138:141], v[150:153]
	v_mfma_f32_16x16x32_bf16 v[154:157], v[146:149], v[158:161], v[154:157]
	v_mfma_f32_16x16x32_bf16 v[142:145], v[146:149], v[162:165], v[142:145]
	v_mfma_f32_16x16x32_bf16 v[146:149], v[146:149], v[166:169], v[98:101]
	ds_read_b128 v[54:57], v208 offset:0x1800
	ds_read_b128 v[236:239], v208 offset:0x3000
	s_waitcnt lgkmcnt(4)
	v_mfma_f32_16x16x32_bf16 v[130:133], v[174:177], v[138:141], v[130:133]
	v_mfma_f32_16x16x32_bf16 v[134:137], v[174:177], v[158:161], v[134:137]
	v_mfma_f32_16x16x32_bf16 v[122:125], v[174:177], v[162:165], v[122:125]
	v_mfma_f32_16x16x32_bf16 v[126:129], v[174:177], v[166:169], v[118:121]
	ds_read_b128 v[58:61], v208 offset:0x2000
	ds_read_b128 v[240:243], v208 offset:0x3800
	s_waitcnt lgkmcnt(5)
	v_mfma_f32_16x16x32_bf16 v[110:113], v[50:53], v[138:141], v[110:113]
	v_mfma_f32_16x16x32_bf16 v[114:117], v[50:53], v[158:161], v[114:117]
	v_mfma_f32_16x16x32_bf16 v[102:105], v[50:53], v[162:165], v[102:105]
	v_mfma_f32_16x16x32_bf16 v[106:109], v[50:53], v[166:169], v[106:109]
	s_waitcnt lgkmcnt(3)
	v_mfma_f32_16x16x32_bf16 v[90:93], v[54:57], v[138:141], v[90:93]
	v_mfma_f32_16x16x32_bf16 v[94:97], v[54:57], v[158:161], v[94:97]
	v_mfma_f32_16x16x32_bf16 v[82:85], v[54:57], v[162:165], v[82:85]
	v_mfma_f32_16x16x32_bf16 v[86:89], v[54:57], v[166:169], v[86:89]
	s_waitcnt lgkmcnt(1)
	v_mfma_f32_16x16x32_bf16 v[70:73], v[58:61], v[138:141], v[70:73]
	v_mfma_f32_16x16x32_bf16 v[74:77], v[58:61], v[158:161], v[74:77]
	v_mfma_f32_16x16x32_bf16 v[62:65], v[58:61], v[162:165], v[62:65]
	v_mfma_f32_16x16x32_bf16 v[66:69], v[58:61], v[166:169], v[66:69]
	s_setprio 0
	s_waitcnt lgkmcnt(0)
	s_waitcnt vmcnt(0)
	s_add_i32 s13, s13, 0x10000
	s_addk_i32 s15, 0x80
	s_cmp_eq_u32 s15, 0x60800
	s_mov_b32 s2, 0x10000
	s_barrier
	s_cbranch_scc0 .Lrot0_top_l
.Lrot0_top_n:
	v_add_u32_e32 v228, s2, v207
	v_add_u32_e32 v229, s2, v204
	ds_read_b128 v[50:53], v229 offset:0
	ds_read_b128 v[54:57], v229 offset:0x800
	ds_read_b128 v[58:61], v229 offset:0x1000
	ds_read_b128 v[78:81], v229 offset:0x1800
	ds_read_b128 v[98:101], v228 offset:0
	ds_read_b128 v[118:121], v228 offset:0x800
	s_setprio 1
	v_mfma_f32_16x16x32_bf16 v[42:45], v[232:235], v[138:141], v[42:45]
	v_mfma_f32_16x16x32_bf16 v[46:49], v[232:235], v[158:161], v[46:49]
	v_mfma_f32_16x16x32_bf16 v[34:37], v[232:235], v[162:165], v[34:37]
	v_mfma_f32_16x16x32_bf16 v[38:41], v[232:235], v[166:169], v[38:41]
	v_mfma_f32_16x16x32_bf16 v[26:29], v[236:239], v[138:141], v[26:29]
	v_mfma_f32_16x16x32_bf16 v[30:33], v[236:239], v[158:161], v[30:33]
	v_mfma_f32_16x16x32_bf16 v[18:21], v[236:239], v[162:165], v[18:21]
	v_mfma_f32_16x16x32_bf16 v[22:25], v[236:239], v[166:169], v[22:25]
	v_mfma_f32_16x16x32_bf16 v[10:13], v[240:243], v[138:141], v[10:13]
	v_mfma_f32_16x16x32_bf16 v[14:17], v[240:243], v[158:161], v[14:17]
	v_mfma_f32_16x16x32_bf16 v[2:5], v[240:243], v[162:165], v[2:5]
	v_mfma_f32_16x16x32_bf16 v[6:9], v[240:243], v[166:169], v[6:9]
	ds_read_b128 v[138:141], v228 offset:0x1000
	v_xor_b32_e32 v208, 64, v228
	s_waitcnt lgkmcnt(2)
	v_mfma_f32_16x16x32_bf16 v[150:153], v[98:101], v[50:53], v[150:153]
	v_mfma_f32_16x16x32_bf16 v[154:157], v[98:101], v[54:57], v[154:157]
	v_mfma_f32_16x16x32_bf16 v[142:145], v[98:101], v[58:61], v[142:145]
	v_mfma_f32_16x16x32_bf16 v[98:101], v[98:101], v[78:81], v[146:149]
	ds_read_b128 v[146:149], v228 offset:0x1800
	s_waitcnt lgkmcnt(2)
	v_mfma_f32_16x16x32_bf16 v[130:133], v[118:121], v[50:53], v[130:133]
	v_mfma_f32_16x16x32_bf16 v[134:137], v[118:121], v[54:57], v[134:137]
	v_mfma_f32_16x16x32_bf16 v[122:125], v[118:121], v[58:61], v[122:125]
	v_mfma_f32_16x16x32_bf16 v[118:121], v[118:121], v[78:81], v[126:129]
	ds_read_b128 v[126:129], v228 offset:0x2000
	s_waitcnt lgkmcnt(2)
	v_mfma_f32_16x16x32_bf16 v[110:113], v[138:141], v[50:53], v[110:113]
	v_mfma_f32_16x16x32_bf16 v[114:117], v[138:141], v[54:57], v[114:117]
	v_mfma_f32_16x16x32_bf16 v[102:105], v[138:141], v[58:61], v[102:105]
	v_mfma_f32_16x16x32_bf16 v[106:109], v[138:141], v[78:81], v[106:109]
	ds_read_b128 v[138:141], v228 offset:0x2800
	s_waitcnt lgkmcnt(2)
	v_mfma_f32_16x16x32_bf16 v[90:93], v[146:149], v[50:53], v[90:93]
	v_mfma_f32_16x16x32_bf16 v[94:97], v[146:149], v[54:57], v[94:97]
	v_mfma_f32_16x16x32_bf16 v[82:85], v[146:149], v[58:61], v[82:85]
	v_mfma_f32_16x16x32_bf16 v[86:89], v[146:149], v[78:81], v[86:89]
	ds_read_b128 v[146:149], v228 offset:0x3000
	s_waitcnt lgkmcnt(2)
	v_mfma_f32_16x16x32_bf16 v[70:73], v[126:129], v[50:53], v[70:73]
	v_mfma_f32_16x16x32_bf16 v[74:77], v[126:129], v[54:57], v[74:77]
	v_mfma_f32_16x16x32_bf16 v[62:65], v[126:129], v[58:61], v[62:65]
	v_mfma_f32_16x16x32_bf16 v[66:69], v[126:129], v[78:81], v[66:69]
	ds_read_b128 v[126:129], v228 offset:0x3800
	s_waitcnt lgkmcnt(2)
	v_xor_b32_e32 v166, 64, v229
	v_mfma_f32_16x16x32_bf16 v[42:45], v[138:141], v[50:53], v[42:45]
	v_mfma_f32_16x16x32_bf16 v[46:49], v[138:141], v[54:57], v[46:49]
	v_mfma_f32_16x16x32_bf16 v[34:37], v[138:141], v[58:61], v[34:37]
	v_mfma_f32_16x16x32_bf16 v[38:41], v[138:141], v[78:81], v[38:41]
	ds_read_b128 v[138:141], v166 offset:0
	ds_read_b128 v[158:161], v166 offset:0x800
	ds_read_b128 v[162:165], v166 offset:0x1000
	s_waitcnt lgkmcnt(4)
	v_mfma_f32_16x16x32_bf16 v[26:29], v[146:149], v[50:53], v[26:29]
	v_mfma_f32_16x16x32_bf16 v[30:33], v[146:149], v[54:57], v[30:33]
	v_mfma_f32_16x16x32_bf16 v[18:21], v[146:149], v[58:61], v[18:21]
	v_mfma_f32_16x16x32_bf16 v[22:25], v[146:149], v[78:81], v[22:25]
	ds_read_b128 v[166:169], v166 offset:0x1800
	ds_read_b128 v[146:149], v208 offset:0
	ds_read_b128 v[174:177], v208 offset:0x800
	s_waitcnt lgkmcnt(6)
	v_mfma_f32_16x16x32_bf16 v[10:13], v[126:129], v[50:53], v[10:13]
	v_mfma_f32_16x16x32_bf16 v[14:17], v[126:129], v[54:57], v[14:17]
	v_mfma_f32_16x16x32_bf16 v[2:5], v[126:129], v[58:61], v[2:5]
	v_mfma_f32_16x16x32_bf16 v[6:9], v[126:129], v[78:81], v[6:9]
	ds_read_b128 v[50:53], v208 offset:0x1000
	ds_read_b128 v[232:235], v208 offset:0x2800
	s_waitcnt lgkmcnt(3)
	v_mfma_f32_16x16x32_bf16 v[150:153], v[146:149], v[138:141], v[150:153]
	v_mfma_f32_16x16x32_bf16 v[154:157], v[146:149], v[158:161], v[154:157]
	v_mfma_f32_16x16x32_bf16 v[142:145], v[146:149], v[162:165], v[142:145]
	v_mfma_f32_16x16x32_bf16 v[146:149], v[146:149], v[166:169], v[98:101]
	ds_read_b128 v[54:57], v208 offset:0x1800
	ds_read_b128 v[236:239], v208 offset:0x3000
	s_waitcnt lgkmcnt(4)
	v_mfma_f32_16x16x32_bf16 v[130:133], v[174:177], v[138:141], v[130:133]
	v_mfma_f32_16x16x32_bf16 v[134:137], v[174:177], v[158:161], v[134:137]
	v_mfma_f32_16x16x32_bf16 v[122:125], v[174:177], v[162:165], v[122:125]
	v_mfma_f32_16x16x32_bf16 v[126:129], v[174:177], v[166:169], v[118:121]
	ds_read_b128 v[58:61], v208 offset:0x2000
	ds_read_b128 v[240:243], v208 offset:0x3800
	s_waitcnt lgkmcnt(5)
	v_mfma_f32_16x16x32_bf16 v[110:113], v[50:53], v[138:141], v[110:113]
	v_mfma_f32_16x16x32_bf16 v[114:117], v[50:53], v[158:161], v[114:117]
	v_mfma_f32_16x16x32_bf16 v[102:105], v[50:53], v[162:165], v[102:105]
	v_mfma_f32_16x16x32_bf16 v[106:109], v[50:53], v[166:169], v[106:109]
	s_waitcnt lgkmcnt(3)
	v_mfma_f32_16x16x32_bf16 v[90:93], v[54:57], v[138:141], v[90:93]
	v_mfma_f32_16x16x32_bf16 v[94:97], v[54:57], v[158:161], v[94:97]
	v_mfma_f32_16x16x32_bf16 v[82:85], v[54:57], v[162:165], v[82:85]
	v_mfma_f32_16x16x32_bf16 v[86:89], v[54:57], v[166:169], v[86:89]
	s_waitcnt lgkmcnt(1)
	v_mfma_f32_16x16x32_bf16 v[70:73], v[58:61], v[138:141], v[70:73]
	v_mfma_f32_16x16x32_bf16 v[74:77], v[58:61], v[158:161], v[74:77]
	v_mfma_f32_16x16x32_bf16 v[62:65], v[58:61], v[162:165], v[62:65]
	v_mfma_f32_16x16x32_bf16 v[66:69], v[58:61], v[166:169], v[66:69]
	s_setprio 0
	s_waitcnt lgkmcnt(0)
	s_add_i32 s13, s13, 0x10000
	s_addk_i32 s15, 0x80
	s_barrier
	v_mfma_f32_16x16x32_bf16 v[42:45], v[232:235], v[138:141], v[42:45]
	v_mfma_f32_16x16x32_bf16 v[46:49], v[232:235], v[158:161], v[46:49]
	v_mfma_f32_16x16x32_bf16 v[34:37], v[232:235], v[162:165], v[34:37]
	v_mfma_f32_16x16x32_bf16 v[38:41], v[232:235], v[166:169], v[38:41]
	v_mfma_f32_16x16x32_bf16 v[26:29], v[236:239], v[138:141], v[26:29]
	v_mfma_f32_16x16x32_bf16 v[30:33], v[236:239], v[158:161], v[30:33]
	v_mfma_f32_16x16x32_bf16 v[18:21], v[236:239], v[162:165], v[18:21]
	v_mfma_f32_16x16x32_bf16 v[22:25], v[236:239], v[166:169], v[22:25]
	v_mfma_f32_16x16x32_bf16 v[10:13], v[240:243], v[138:141], v[10:13]
	v_mfma_f32_16x16x32_bf16 v[14:17], v[240:243], v[158:161], v[14:17]
	v_mfma_f32_16x16x32_bf16 v[2:5], v[240:243], v[162:165], v[2:5]
	v_mfma_f32_16x16x32_bf16 v[6:9], v[240:243], v[166:169], v[6:9]
	s_nop 7
	s_nop 7
	s_nop 3
